# in-proj GEMM tail split: round 7 (128 tiles) shared by CU pairs, each computing one 128-column half with the bj=1 MFMAs removed; on top of dskew
# speedup vs baseline: 1.0180x; 1.0101x over previous
;     __host__ __device__ bool next(int i, Unit& u) const {
;         const long L = (long)i * G + c; if (L >= nwg) return false;
;         int wgid = (int)L; { const int q = nwg / NXCD, r = nwg % NXCD, xcd = wgid % NXCD, off = wgid / NXCD; wgid = (xcd < r ? xcd * (q + 1) : r * (q + 1) + (xcd - r) * q) + off; }
;         const int nig = WGM * nN, gid = wgid / nig, fm = gid * WGM, gsz = (nM - fm) < WGM ? (nM - fm) : WGM;
;         u.pm = fm + ((wgid % nig) % gsz); u.pn = (wgid % nig) / gsz; return true;
; template <class Epi, class Sched, bool ALIGN_EPI = false, bool SP2 = false>
; __device__ __forceinline__ void gemm_phase(PG8_LAS unsigned char* lds, const Gemm g, const Sched& S, const Epi& E) {
;     ...
;     for (;;) {
;         const bool has_next = S.next(ui + 1, nxt);
;         const char* nA = has_next ? (const char*)g.A + (size_t)nxt.pm * tstep : cA; const char* nB = has_next ? (const char*)g.Bt + (size_t)nxt.pn * tstep : cB;
;         for (int t = 0; t < nt; t += 2) {
;             const bool last = (t == nt - 2);
;             const char* a1 = cA + (size_t)(t + 1) * kstep;
;             const char* a2 = last ? nA : cA + (size_t)(t + 2) * kstep; const char* b2 = last ? nB : cB + (size_t)(t + 2) * kstep;
;             const char* a3 = a2 + kstep; const char* b3 = b2 + kstep;
;             if (last && has_next) S.a_ready(nxt);
.LBB0_211:
	s_add_i32 s27, s27, 1
	s_mul_i32 s15, s27, s12
	s_mul_hi_u32 s17, s27, s98
	s_add_i32 s17, s17, s15
	s_mul_i32 s15, s27, s98
	s_add_u32 s20, s15, s49
	s_addc_u32 s21, s17, s7
	s_cmp_lg_u32 s27, 6
	s_cbranch_scc1 .Ltail_a
	s_and_b32 s20, s49, 0x7f
	s_addk_i32 s20, 0x600
	s_mov_b32 s21, 0
.Ltail_a:
	v_mov_b64_e32 v[2:3], 0x680
	v_cmp_gt_i64_e32 vcc, s[20:21], v[240:241]
	v_cmp_lt_i64_e64 s[38:39], s[20:21], v[2:3]
	s_cbranch_vccnz .LBB0_213
	s_ashr_i32 s15, s20, 31
	s_lshr_b32 s15, s15, 29
	s_add_i32 s15, s20, s15
	s_ashr_i32 s16, s15, 3
	s_and_b32 s15, s15, -8
	s_sub_i32 s15, s20, s15
	s_cmp_lt_i32 s15, 0
	s_movk_i32 s17, 0xd1
	s_cselect_b32 s17, s17, 0xd0
	s_mul_i32 s15, s15, s17
	s_add_i32 s15, s15, s16
	s_mul_hi_i32 s16, s15, 0x4ec4ec4f
	s_lshr_b32 s17, s16, 31
	s_ashr_i32 s16, s16, 5
	s_add_i32 s16, s16, s17
	s_lshl_b32 s17, s16, 2
	s_sub_i32 s18, 64, s17
	s_min_i32 s18, s18, 4
	s_abs_i32 s19, s18
	v_cvt_f32_u32_e32 v2, s19
	s_sub_i32 s21, 0, s19
	s_mulk_i32 s16, 0x68
	s_sub_i32 s15, s15, s16
	v_rcp_iflag_f32_e32 v2, v2
	s_abs_i32 s16, s15
	s_xor_b32 s20, s15, s18
	s_ashr_i32 s20, s20, 31
	v_mul_f32_e32 v2, 0x4f7ffffe, v2
	v_cvt_u32_f32_e32 v2, v2
	s_nop 0
	v_readfirstlane_b32 s22, v2
	s_mul_i32 s21, s21, s22
	s_mul_hi_u32 s21, s22, s21
	s_add_i32 s22, s22, s21
	s_mul_hi_u32 s21, s16, s22
	s_mul_i32 s22, s21, s19
	s_sub_i32 s16, s16, s22
	s_add_i32 s23, s21, 1
	s_sub_i32 s22, s16, s19
	s_cmp_ge_u32 s16, s19
	s_cselect_b32 s21, s23, s21
	s_cselect_b32 s16, s22, s16
	s_add_i32 s22, s21, 1
	s_cmp_ge_u32 s16, s19
	s_cselect_b32 s16, s22, s21
	s_xor_b32 s16, s16, s20
	s_sub_i32 s16, s16, s20
	s_mul_i32 s18, s16, s18
	s_sub_i32 s15, s15, s18
	s_add_i32 s18, s17, s15
.LBB0_213:
	s_ashr_i32 s19, s18, 31
	s_lshl_b64 s[20:21], s[18:19], 20
	s_add_u32 s20, s30, s20
	s_addc_u32 s21, s31, s21
	s_and_b64 s[22:23], s[38:39], exec
	s_cselect_b32 s15, s21, s43
	s_cselect_b32 s19, s20, s42
	s_ashr_i32 s17, s16, 31
	s_lshl_b64 s[22:23], s[16:17], 20
	s_add_u32 s22, s4, s22
	s_addc_u32 s23, s5, s23
	s_cmp_lg_u32 s27, 6
	s_cbranch_scc1 .Ltail_b
	s_lshr_b32 s34, s49, 7
	s_lshl_b32 s34, s34, 19
	s_add_u32 s22, s22, s34
	s_addc_u32 s23, s23, 0
.Ltail_b:
	s_and_b64 s[34:35], s[38:39], exec
	s_cselect_b32 s17, s23, s41
	s_cselect_b32 s37, s22, s40
	s_add_u32 s34, s42, 0x80080
	s_addc_u32 s35, s43, 0
	s_add_u32 s44, s40, 0x100
	v_mov_b32_e32 v2, 0
	s_addc_u32 s45, s41, 0
	s_mov_b32 s46, -2
	v_mov_b32_e32 v3, v2
	v_mov_b32_e32 v4, v2
	v_mov_b32_e32 v5, v2
	v_mov_b32_e32 v6, v2
	v_mov_b32_e32 v7, v2
	v_mov_b32_e32 v8, v2
	v_mov_b32_e32 v9, v2
	v_mov_b32_e32 v18, v2
	v_mov_b32_e32 v19, v2
	v_mov_b32_e32 v20, v2
	v_mov_b32_e32 v21, v2
	v_mov_b32_e32 v22, v2
	v_mov_b32_e32 v23, v2
	v_mov_b32_e32 v24, v2
	v_mov_b32_e32 v25, v2
	v_mov_b32_e32 v34, v2
	v_mov_b32_e32 v35, v2
	v_mov_b32_e32 v36, v2
	v_mov_b32_e32 v37, v2
	v_mov_b32_e32 v38, v2
	v_mov_b32_e32 v39, v2
	v_mov_b32_e32 v40, v2
	v_mov_b32_e32 v41, v2
	v_mov_b32_e32 v50, v2
	v_mov_b32_e32 v51, v2
	v_mov_b32_e32 v52, v2
	v_mov_b32_e32 v53, v2
	v_mov_b32_e32 v54, v2
	v_mov_b32_e32 v55, v2
	v_mov_b32_e32 v56, v2
	v_mov_b32_e32 v57, v2
	v_mov_b32_e32 v10, v2
	v_mov_b32_e32 v11, v2
	v_mov_b32_e32 v12, v2
	v_mov_b32_e32 v13, v2
	v_mov_b32_e32 v14, v2
	v_mov_b32_e32 v15, v2
	v_mov_b32_e32 v16, v2
	v_mov_b32_e32 v17, v2
	v_mov_b32_e32 v26, v2
	v_mov_b32_e32 v27, v2
	v_mov_b32_e32 v28, v2
	v_mov_b32_e32 v29, v2
	v_mov_b32_e32 v30, v2
	v_mov_b32_e32 v31, v2
	v_mov_b32_e32 v32, v2
	v_mov_b32_e32 v33, v2
	v_mov_b32_e32 v42, v2
	v_mov_b32_e32 v43, v2
	v_mov_b32_e32 v44, v2
	v_mov_b32_e32 v45, v2
	v_mov_b32_e32 v46, v2
	v_mov_b32_e32 v47, v2
	v_mov_b32_e32 v48, v2
	v_mov_b32_e32 v49, v2
	v_mov_b32_e32 v58, v2
	v_mov_b32_e32 v59, v2
	v_mov_b32_e32 v60, v2
	v_mov_b32_e32 v61, v2
	v_mov_b32_e32 v62, v2
	v_mov_b32_e32 v63, v2
	v_mov_b32_e32 v64, v2
	v_mov_b32_e32 v65, v2
	v_mov_b32_e32 v66, v2
	v_mov_b32_e32 v67, v2
	v_mov_b32_e32 v68, v2
	v_mov_b32_e32 v69, v2
	v_mov_b32_e32 v70, v2
	v_mov_b32_e32 v71, v2
	v_mov_b32_e32 v72, v2
	v_mov_b32_e32 v73, v2
	v_mov_b32_e32 v82, v2
	v_mov_b32_e32 v83, v2
	v_mov_b32_e32 v84, v2
	v_mov_b32_e32 v85, v2
	v_mov_b32_e32 v86, v2
	v_mov_b32_e32 v87, v2
	v_mov_b32_e32 v88, v2
	v_mov_b32_e32 v89, v2
	v_mov_b32_e32 v98, v2
	v_mov_b32_e32 v99, v2
	v_mov_b32_e32 v100, v2
	v_mov_b32_e32 v101, v2
	v_mov_b32_e32 v102, v2
	v_mov_b32_e32 v103, v2
	v_mov_b32_e32 v104, v2
	v_mov_b32_e32 v105, v2
	v_mov_b32_e32 v122, v2
	v_mov_b32_e32 v123, v2
	v_mov_b32_e32 v124, v2
	v_mov_b32_e32 v125, v2
	v_mov_b32_e32 v126, v2
	v_mov_b32_e32 v127, v2
	v_mov_b32_e32 v128, v2
	v_mov_b32_e32 v129, v2
	v_mov_b32_e32 v74, v2
	v_mov_b32_e32 v75, v2
	v_mov_b32_e32 v76, v2
	v_mov_b32_e32 v77, v2
	v_mov_b32_e32 v78, v2
	v_mov_b32_e32 v79, v2
	v_mov_b32_e32 v80, v2
	v_mov_b32_e32 v81, v2
	v_mov_b32_e32 v90, v2
	v_mov_b32_e32 v91, v2
	v_mov_b32_e32 v92, v2
	v_mov_b32_e32 v93, v2
	v_mov_b32_e32 v94, v2
	v_mov_b32_e32 v95, v2
	v_mov_b32_e32 v96, v2
	v_mov_b32_e32 v97, v2
	v_mov_b32_e32 v106, v2
	v_mov_b32_e32 v107, v2
	v_mov_b32_e32 v108, v2
	v_mov_b32_e32 v109, v2
	v_mov_b32_e32 v110, v2
	v_mov_b32_e32 v111, v2
	v_mov_b32_e32 v112, v2
	v_mov_b32_e32 v113, v2
	v_mov_b32_e32 v138, v2
	v_mov_b32_e32 v139, v2
	v_mov_b32_e32 v140, v2
	v_mov_b32_e32 v141, v2
	v_mov_b32_e32 v142, v2
	v_mov_b32_e32 v143, v2
	v_mov_b32_e32 v144, v2
	v_mov_b32_e32 v145, v2
	s_cmp_eq_u32 s27, 7
	s_cbranch_scc1 .Ltail_loop

; __device__ __forceinline__ unsigned cvt_pk_bf16(float lo, float hi) { unsigned r; asm volatile("v_cvt_pk_bf16_f32 %0, %1, %2" : "=v"(r) : "v"(lo), "v"(hi)); return r; }
;     __device__ __forceinline__ void operator()(const f32x4 (&acc)[2][2][4][2], const Unit& u, int wr, int wc, int fr, int fq) const {
;         const int row0 = u.pm * BM + wr * 64 + fr, col0 = wc * 32 + 8 * fq;
; #pragma unroll
;         for (int ai = 0; ai < 2; ++ai) {
;             f32x4 pa[4], pb[4];
; #pragma unroll
;             for (int m = 0; m < 4; ++m) { const f32x4* pp = (const f32x4*)(rowsq + (size_t)(row0 + ai * HALF + m * 16) * 32 + 8 * fq); pa[m] = pp[0]; pb[m] = pp[1]; }
; #pragma unroll
;             for (int m = 0; m < 4; ++m) { const int row = row0 + ai * HALF + m * 16; const f32x4 a = pa[m], b = pb[m];
;                 float sq = ((a[0] + a[1]) + (a[2] + a[3])) + ((b[0] + b[1]) + (b[2] + b[3])); sq += __shfl_xor(sq, 16); sq += __shfl_xor(sq, 32);
;                 const float rs = __builtin_amdgcn_rsqf(sq * inv_k + eps);
; #pragma unroll
;                 for (int bj = 0; bj < 2; ++bj) { const f32x4 v0 = acc[ai][bj][m][0] * rs, v1 = acc[ai][bj][m][1] * rs;
;                     u32x4 w; w.x = cvt_pk_bf16(v0[0], v0[1]); w.y = cvt_pk_bf16(v0[2], v0[3]); w.z = cvt_pk_bf16(v1[0], v1[1]); w.w = cvt_pk_bf16(v1[2], v1[3]);
;                     *(u32x4*)(O + ((size_t)(u.pn * 2 + bj) * Mrows + row) * HALF + col0) = w; } }
;             asm volatile("" ::: "memory"); }
.Ltail_join:
	s_and_b64 vcc, exec, s[2:3]
	s_cbranch_vccz .LBB0_217
	s_barrier
.LBB0_217:
	v_cmp_lt_i32_e32 vcc, v224, v219
	v_lshl_add_u32 v168, s36, 8, v176
	v_ashrrev_i32_e32 v169, 31, v168
	v_cndmask_b32_e32 v114, v218, v224, vcc
	v_cmp_lt_i32_e32 vcc, v225, v219
	v_lshlrev_b32_e32 v180, 2, v114
	v_or_b32_e32 v174, 16, v168
	v_cndmask_b32_e32 v114, v218, v225, vcc
	v_lshlrev_b32_e32 v179, 2, v114
	v_lshlrev_b64 v[114:115], 7, v[168:169]
	v_lshl_add_u64 v[114:115], v[162:163], 0, v[114:115]
	global_load_dwordx4 v[182:185], v[114:115], off
	global_load_dwordx4 v[186:189], v[114:115], off offset:16
	v_ashrrev_i32_e32 v175, 31, v174
	v_lshlrev_b64 v[114:115], 7, v[174:175]
	v_lshl_add_u64 v[114:115], v[162:163], 0, v[114:115]
	global_load_dwordx4 v[146:149], v[114:115], off
	global_load_dwordx4 v[150:153], v[114:115], off offset:16
	v_or_b32_e32 v172, 32, v168
	v_ashrrev_i32_e32 v173, 31, v172
	v_lshlrev_b64 v[114:115], 7, v[172:173]
	v_lshl_add_u64 v[114:115], v[162:163], 0, v[114:115]
	global_load_dwordx4 v[134:137], v[114:115], off
	global_load_dwordx4 v[130:133], v[114:115], off offset:16
	v_or_b32_e32 v170, 48, v168
	v_ashrrev_i32_e32 v171, 31, v170
	v_lshlrev_b64 v[114:115], 7, v[170:171]
	v_lshl_add_u64 v[114:115], v[162:163], 0, v[114:115]
	global_load_dwordx4 v[118:121], v[114:115], off
	s_nop 0
	global_load_dwordx4 v[114:117], v[114:115], off offset:16
	s_lshl_b32 s14, s14, 1
	s_cmp_eq_u32 s27, 7
	s_cselect_b64 s[80:81], 0, -1
	s_cbranch_scc0 .Ltail_c
	s_lshr_b32 s15, s49, 7
	s_add_i32 s14, s14, s15
.Ltail_c:
	s_ashr_i32 s15, s14, 31
	s_lshl_b64 s[34:35], s[14:15], 14
	s_or_b32 s14, s14, 1
	s_ashr_i32 s15, s14, 31
	s_lshl_b64 s[36:37], s[14:15], 14
	s_andn2_b64 vcc, exec, s[38:39]
	s_waitcnt vmcnt(0)
	v_mov_b32_e32 v190, v182
	v_mov_b32_e32 v191, v186
	v_mov_b32_e32 v186, v183
	v_pk_add_f32 v[182:183], v[190:191], v[186:187]
	v_mov_b32_e32 v186, v184
	v_mov_b32_e32 v187, v188
	v_mov_b32_e32 v188, v185
	v_pk_add_f32 v[184:185], v[186:187], v[188:189]
	s_nop 0
	v_pk_add_f32 v[182:183], v[182:183], v[184:185]
	s_nop 0
	v_add_f32_e32 v181, v182, v183
	ds_bpermute_b32 v182, v180, v181
	s_waitcnt lgkmcnt(0)
	v_add_f32_e32 v181, v181, v182
	ds_bpermute_b32 v182, v179, v181
	s_waitcnt lgkmcnt(0)
	v_add_f32_e32 v181, v181, v182
	v_fmamk_f32 v181, v181, 0x3a000000, v215
	v_rsq_f32_e32 v182, v181
	s_nop 0
	v_pk_mul_f32 v[142:143], v[142:143], v[182:183] op_sel_hi:[1,0]
	v_pk_mul_f32 v[184:185], v[140:141], v[182:183] op_sel_hi:[1,0]
	v_pk_mul_f32 v[140:141], v[138:139], v[182:183] op_sel_hi:[1,0]
	v_cvt_pk_bf16_f32 v138, v142, v143
	v_lshl_add_u64 v[142:143], s[34:35], 0, v[168:169]
	v_lshlrev_b64 v[142:143], 8, v[142:143]
	v_pk_mul_f32 v[144:145], v[144:145], v[182:183] op_sel_hi:[1,0]
	v_lshl_add_u64 v[142:143], v[160:161], 0, v[142:143]
	v_cvt_pk_bf16_f32 v139, v144, v145
	v_pk_mul_f32 v[126:127], v[126:127], v[182:183] op_sel_hi:[1,0]
	v_cvt_pk_bf16_f32 v140, v140, v141
	v_cvt_pk_bf16_f32 v141, v184, v185
	global_store_dwordx4 v[142:143], v[138:141], off
	v_pk_mul_f32 v[128:129], v[128:129], v[182:183] op_sel_hi:[1,0]
	s_nop 0
	v_pk_mul_f32 v[138:139], v[124:125], v[182:183] op_sel_hi:[1,0]
	v_pk_mul_f32 v[124:125], v[122:123], v[182:183] op_sel_hi:[1,0]
	v_cvt_pk_bf16_f32 v122, v126, v127
	v_lshl_add_u64 v[126:127], s[36:37], 0, v[168:169]
	v_lshlrev_b64 v[126:127], 8, v[126:127]
	v_cvt_pk_bf16_f32 v123, v128, v129
	v_cvt_pk_bf16_f32 v124, v124, v125
	v_cvt_pk_bf16_f32 v125, v138, v139
	v_lshl_add_u64 v[126:127], v[160:161], 0, v[126:127]
	s_mov_b64 exec, s[80:81]
	global_store_dwordx4 v[126:127], v[122:125], off
	s_mov_b64 exec, -1
	s_nop 1
	v_mov_b32_e32 v122, v146
	v_mov_b32_e32 v123, v150
	v_mov_b32_e32 v150, v147
	v_mov_b32_e32 v124, v148
	v_mov_b32_e32 v125, v152
	v_mov_b32_e32 v152, v149
	v_pk_add_f32 v[122:123], v[122:123], v[150:151]
	v_pk_add_f32 v[124:125], v[124:125], v[152:153]
	s_nop 0
	v_pk_add_f32 v[122:123], v[122:123], v[124:125]
	s_nop 0
	v_add_f32_e32 v122, v122, v123
	ds_bpermute_b32 v123, v180, v122
	s_waitcnt lgkmcnt(0)
	v_add_f32_e32 v122, v122, v123
	ds_bpermute_b32 v123, v179, v122
	s_waitcnt lgkmcnt(0)
	v_add_f32_e32 v122, v122, v123
	v_fmamk_f32 v122, v122, 0x3a000000, v215
	v_rsq_f32_e32 v122, v122
	s_nop 0
	v_pk_mul_f32 v[110:111], v[110:111], v[122:123] op_sel_hi:[1,0]
	v_pk_mul_f32 v[124:125], v[108:109], v[122:123] op_sel_hi:[1,0]
	v_pk_mul_f32 v[108:109], v[106:107], v[122:123] op_sel_hi:[1,0]
	v_cvt_pk_bf16_f32 v106, v110, v111
	v_lshl_add_u64 v[110:111], s[34:35], 0, v[174:175]
	v_lshlrev_b64 v[110:111], 8, v[110:111]
	v_pk_mul_f32 v[112:113], v[112:113], v[122:123] op_sel_hi:[1,0]
	v_lshl_add_u64 v[110:111], v[160:161], 0, v[110:111]
	v_cvt_pk_bf16_f32 v107, v112, v113
	v_pk_mul_f32 v[102:103], v[102:103], v[122:123] op_sel_hi:[1,0]
	v_cvt_pk_bf16_f32 v108, v108, v109
	v_cvt_pk_bf16_f32 v109, v124, v125
	global_store_dwordx4 v[110:111], v[106:109], off
	v_pk_mul_f32 v[104:105], v[104:105], v[122:123] op_sel_hi:[1,0]
	s_nop 0
	v_pk_mul_f32 v[106:107], v[100:101], v[122:123] op_sel_hi:[1,0]
	v_pk_mul_f32 v[100:101], v[98:99], v[122:123] op_sel_hi:[1,0]
	v_cvt_pk_bf16_f32 v98, v102, v103
	v_lshl_add_u64 v[102:103], s[36:37], 0, v[174:175]
	v_lshlrev_b64 v[102:103], 8, v[102:103]
	v_cvt_pk_bf16_f32 v99, v104, v105
	v_cvt_pk_bf16_f32 v100, v100, v101
	v_cvt_pk_bf16_f32 v101, v106, v107
	v_lshl_add_u64 v[102:103], v[160:161], 0, v[102:103]
	s_mov_b64 exec, s[80:81]
	global_store_dwordx4 v[102:103], v[98:101], off
	s_mov_b64 exec, -1
	v_add_u32_e32 v104, 0x80, v168
	v_ashrrev_i32_e32 v105, 31, v104
	v_mov_b32_e32 v98, v134
	v_mov_b32_e32 v99, v130
	v_mov_b32_e32 v130, v135
	v_mov_b32_e32 v100, v136
	v_mov_b32_e32 v101, v132
	v_mov_b32_e32 v132, v137
	v_pk_add_f32 v[98:99], v[98:99], v[130:131]
	v_pk_add_f32 v[100:101], v[100:101], v[132:133]
	s_nop 0
	v_pk_add_f32 v[98:99], v[98:99], v[100:101]
	s_nop 0
	v_add_f32_e32 v98, v98, v99
	ds_bpermute_b32 v99, v180, v98
	s_waitcnt lgkmcnt(0)
; __device__ __forceinline__ unsigned cvt_pk_bf16(float lo, float hi) { unsigned r; asm volatile("v_cvt_pk_bf16_f32 %0, %1, %2" : "=v"(r) : "v"(lo), "v"(hi)); return r; }
;     __device__ __forceinline__ void operator()(const f32x4 (&acc)[2][2][4][2], const Unit& u, int wr, int wc, int fr, int fq) const {
;         const int row0 = u.pm * BM + wr * 64 + fr, col0 = wc * 32 + 8 * fq;
; #pragma unroll
;         for (int ai = 0; ai < 2; ++ai) {
;             f32x4 pa[4], pb[4];
; #pragma unroll
;             for (int m = 0; m < 4; ++m) { const f32x4* pp = (const f32x4*)(rowsq + (size_t)(row0 + ai * HALF + m * 16) * 32 + 8 * fq); pa[m] = pp[0]; pb[m] = pp[1]; }
; #pragma unroll
;             for (int m = 0; m < 4; ++m) { const int row = row0 + ai * HALF + m * 16; const f32x4 a = pa[m], b = pb[m];
;                 float sq = ((a[0] + a[1]) + (a[2] + a[3])) + ((b[0] + b[1]) + (b[2] + b[3])); sq += __shfl_xor(sq, 16); sq += __shfl_xor(sq, 32);
;                 const float rs = __builtin_amdgcn_rsqf(sq * inv_k + eps);
; #pragma unroll
;                 for (int bj = 0; bj < 2; ++bj) { const f32x4 v0 = acc[ai][bj][m][0] * rs, v1 = acc[ai][bj][m][1] * rs;
;                     u32x4 w; w.x = cvt_pk_bf16(v0[0], v0[1]); w.y = cvt_pk_bf16(v0[2], v0[3]); w.z = cvt_pk_bf16(v1[0], v1[1]); w.w = cvt_pk_bf16(v1[2], v1[3]);
;                     *(u32x4*)(O + ((size_t)(u.pn * 2 + bj) * Mrows + row) * HALF + col0) = w; } }
;             asm volatile("" ::: "memory"); }
	v_add_f32_e32 v98, v98, v99
	ds_bpermute_b32 v99, v179, v98
	s_waitcnt lgkmcnt(0)
	v_add_f32_e32 v98, v98, v99
	v_fmamk_f32 v98, v98, 0x3a000000, v215
	v_rsq_f32_e32 v98, v98
	s_nop 0
	v_pk_mul_f32 v[94:95], v[94:95], v[98:99] op_sel_hi:[1,0]
	v_pk_mul_f32 v[100:101], v[92:93], v[98:99] op_sel_hi:[1,0]
	v_pk_mul_f32 v[92:93], v[90:91], v[98:99] op_sel_hi:[1,0]
	v_cvt_pk_bf16_f32 v90, v94, v95
	v_lshl_add_u64 v[94:95], s[34:35], 0, v[172:173]
	v_lshlrev_b64 v[94:95], 8, v[94:95]
	v_pk_mul_f32 v[96:97], v[96:97], v[98:99] op_sel_hi:[1,0]
	v_lshl_add_u64 v[94:95], v[160:161], 0, v[94:95]
	v_cvt_pk_bf16_f32 v91, v96, v97
	v_pk_mul_f32 v[86:87], v[86:87], v[98:99] op_sel_hi:[1,0]
	v_cvt_pk_bf16_f32 v92, v92, v93
	v_cvt_pk_bf16_f32 v93, v100, v101
	global_store_dwordx4 v[94:95], v[90:93], off
	v_pk_mul_f32 v[88:89], v[88:89], v[98:99] op_sel_hi:[1,0]
	s_nop 0
	v_pk_mul_f32 v[90:91], v[84:85], v[98:99] op_sel_hi:[1,0]
	v_pk_mul_f32 v[84:85], v[82:83], v[98:99] op_sel_hi:[1,0]
	v_cvt_pk_bf16_f32 v82, v86, v87
	v_lshl_add_u64 v[86:87], s[36:37], 0, v[172:173]
	v_lshlrev_b64 v[86:87], 8, v[86:87]
	v_cvt_pk_bf16_f32 v83, v88, v89
	v_cvt_pk_bf16_f32 v84, v84, v85
	v_cvt_pk_bf16_f32 v85, v90, v91
	v_lshl_add_u64 v[86:87], v[160:161], 0, v[86:87]
	s_mov_b64 exec, s[80:81]
	global_store_dwordx4 v[86:87], v[82:85], off
	s_mov_b64 exec, -1
	v_add_u32_e32 v86, 0x90, v168
	v_ashrrev_i32_e32 v87, 31, v86
	v_mov_b32_e32 v82, v118
	v_mov_b32_e32 v83, v114
	v_mov_b32_e32 v114, v119
	v_mov_b32_e32 v84, v120
	v_mov_b32_e32 v85, v116
	v_mov_b32_e32 v116, v121
	v_pk_add_f32 v[82:83], v[82:83], v[114:115]
	v_pk_add_f32 v[84:85], v[84:85], v[116:117]
	s_nop 0
	v_pk_add_f32 v[82:83], v[82:83], v[84:85]
	s_nop 0
	v_add_f32_e32 v82, v82, v83
	ds_bpermute_b32 v83, v180, v82
	s_waitcnt lgkmcnt(0)
	v_add_f32_e32 v82, v82, v83
	ds_bpermute_b32 v83, v179, v82
	s_waitcnt lgkmcnt(0)
	v_add_f32_e32 v82, v82, v83
	v_fmamk_f32 v82, v82, 0x3a000000, v215
	v_rsq_f32_e32 v82, v82
	s_nop 0
	v_pk_mul_f32 v[78:79], v[78:79], v[82:83] op_sel_hi:[1,0]
	v_pk_mul_f32 v[84:85], v[76:77], v[82:83] op_sel_hi:[1,0]
	v_pk_mul_f32 v[76:77], v[74:75], v[82:83] op_sel_hi:[1,0]
	v_cvt_pk_bf16_f32 v74, v78, v79
	v_lshl_add_u64 v[78:79], s[34:35], 0, v[170:171]
	v_lshlrev_b64 v[78:79], 8, v[78:79]
	v_pk_mul_f32 v[80:81], v[80:81], v[82:83] op_sel_hi:[1,0]
	v_lshl_add_u64 v[78:79], v[160:161], 0, v[78:79]
	v_cvt_pk_bf16_f32 v75, v80, v81
	v_pk_mul_f32 v[70:71], v[70:71], v[82:83] op_sel_hi:[1,0]
	v_cvt_pk_bf16_f32 v76, v76, v77
	v_cvt_pk_bf16_f32 v77, v84, v85
	global_store_dwordx4 v[78:79], v[74:77], off
	v_pk_mul_f32 v[72:73], v[72:73], v[82:83] op_sel_hi:[1,0]
	v_add_u32_e32 v84, 0xa0, v168
	v_pk_mul_f32 v[74:75], v[68:69], v[82:83] op_sel_hi:[1,0]
	v_pk_mul_f32 v[68:69], v[66:67], v[82:83] op_sel_hi:[1,0]
	v_cvt_pk_bf16_f32 v66, v70, v71
	v_lshl_add_u64 v[70:71], s[36:37], 0, v[170:171]
	v_lshlrev_b64 v[70:71], 8, v[70:71]
	v_cvt_pk_bf16_f32 v67, v72, v73
	v_lshl_add_u64 v[70:71], v[160:161], 0, v[70:71]
	v_cvt_pk_bf16_f32 v68, v68, v69
	v_cvt_pk_bf16_f32 v69, v74, v75
	s_mov_b64 exec, s[80:81]
	global_store_dwordx4 v[70:71], v[66:69], off
	s_mov_b64 exec, -1
	v_ashrrev_i32_e32 v85, 31, v84
	v_add_u32_e32 v82, 0xb0, v168
	v_lshlrev_b64 v[66:67], 7, v[104:105]
	v_lshl_add_u64 v[66:67], v[162:163], 0, v[66:67]
	global_load_dwordx4 v[88:91], v[66:67], off
	global_load_dwordx4 v[92:95], v[66:67], off offset:16
	v_lshlrev_b64 v[66:67], 7, v[86:87]
	v_lshl_add_u64 v[66:67], v[162:163], 0, v[66:67]
	global_load_dwordx4 v[96:99], v[66:67], off
	global_load_dwordx4 v[100:103], v[66:67], off offset:16
	v_lshlrev_b64 v[66:67], 7, v[84:85]
	v_lshl_add_u64 v[66:67], v[162:163], 0, v[66:67]
	global_load_dwordx4 v[78:81], v[66:67], off
	global_load_dwordx4 v[74:77], v[66:67], off offset:16
	v_ashrrev_i32_e32 v83, 31, v82
	v_lshlrev_b64 v[66:67], 7, v[82:83]
	v_lshl_add_u64 v[66:67], v[162:163], 0, v[66:67]
	global_load_dwordx4 v[70:73], v[66:67], off
	s_nop 0
	global_load_dwordx4 v[66:69], v[66:67], off offset:16
	s_waitcnt vmcnt(7)
	v_mov_b32_e32 v106, v88
	s_waitcnt vmcnt(6)
	v_mov_b32_e32 v107, v92
	v_mov_b32_e32 v92, v89
	v_pk_add_f32 v[88:89], v[106:107], v[92:93]
	v_mov_b32_e32 v92, v90
	v_mov_b32_e32 v93, v94
	v_mov_b32_e32 v94, v91
	v_pk_add_f32 v[90:91], v[92:93], v[94:95]
	s_nop 0
	v_pk_add_f32 v[88:89], v[88:89], v[90:91]
	s_nop 0
	v_add_f32_e32 v88, v88, v89
	ds_bpermute_b32 v89, v180, v88
	s_waitcnt lgkmcnt(0)
	v_add_f32_e32 v88, v88, v89
	ds_bpermute_b32 v89, v179, v88
	s_waitcnt lgkmcnt(0)
	v_add_f32_e32 v88, v88, v89
	v_fmamk_f32 v88, v88, 0x3a000000, v215
	v_rsq_f32_e32 v88, v88
	s_nop 0
	v_pk_mul_f32 v[62:63], v[62:63], v[88:89] op_sel_hi:[1,0]
	v_pk_mul_f32 v[90:91], v[60:61], v[88:89] op_sel_hi:[1,0]
	v_pk_mul_f32 v[60:61], v[58:59], v[88:89] op_sel_hi:[1,0]
	v_cvt_pk_bf16_f32 v58, v62, v63
	v_lshl_add_u64 v[62:63], s[34:35], 0, v[104:105]
	v_lshlrev_b64 v[62:63], 8, v[62:63]
	v_pk_mul_f32 v[64:65], v[64:65], v[88:89] op_sel_hi:[1,0]
	v_lshl_add_u64 v[62:63], v[160:161], 0, v[62:63]
	v_cvt_pk_bf16_f32 v59, v64, v65
	v_pk_mul_f32 v[54:55], v[54:55], v[88:89] op_sel_hi:[1,0]
	v_cvt_pk_bf16_f32 v60, v60, v61
	v_cvt_pk_bf16_f32 v61, v90, v91
	global_store_dwordx4 v[62:63], v[58:61], off
	v_pk_mul_f32 v[56:57], v[56:57], v[88:89] op_sel_hi:[1,0]
	s_nop 0
	v_pk_mul_f32 v[58:59], v[52:53], v[88:89] op_sel_hi:[1,0]
	v_pk_mul_f32 v[52:53], v[50:51], v[88:89] op_sel_hi:[1,0]
	v_cvt_pk_bf16_f32 v50, v54, v55
	v_lshl_add_u64 v[54:55], s[36:37], 0, v[104:105]
	v_lshlrev_b64 v[54:55], 8, v[54:55]
	v_cvt_pk_bf16_f32 v51, v56, v57
	v_cvt_pk_bf16_f32 v52, v52, v53
	v_cvt_pk_bf16_f32 v53, v58, v59
	v_lshl_add_u64 v[54:55], v[160:161], 0, v[54:55]
	s_mov_b64 exec, s[80:81]
	global_store_dwordx4 v[54:55], v[50:53], off
	s_mov_b64 exec, -1
	s_waitcnt vmcnt(7)
; __device__ __forceinline__ unsigned cvt_pk_bf16(float lo, float hi) { unsigned r; asm volatile("v_cvt_pk_bf16_f32 %0, %1, %2" : "=v"(r) : "v"(lo), "v"(hi)); return r; }
; #define PG8_BAR __builtin_amdgcn_s_barrier()
;     __device__ __forceinline__ void operator()(const f32x4 (&acc)[2][2][4][2], const Unit& u, int wr, int wc, int fr, int fq) const {
;         const int row0 = u.pm * BM + wr * 64 + fr, col0 = wc * 32 + 8 * fq;
; #pragma unroll
;         for (int ai = 0; ai < 2; ++ai) {
;             f32x4 pa[4], pb[4];
; #pragma unroll
;             for (int m = 0; m < 4; ++m) { const f32x4* pp = (const f32x4*)(rowsq + (size_t)(row0 + ai * HALF + m * 16) * 32 + 8 * fq); pa[m] = pp[0]; pb[m] = pp[1]; }
; #pragma unroll
;             for (int m = 0; m < 4; ++m) { const int row = row0 + ai * HALF + m * 16; const f32x4 a = pa[m], b = pb[m];
;                 float sq = ((a[0] + a[1]) + (a[2] + a[3])) + ((b[0] + b[1]) + (b[2] + b[3])); sq += __shfl_xor(sq, 16); sq += __shfl_xor(sq, 32);
;                 const float rs = __builtin_amdgcn_rsqf(sq * inv_k + eps);
; #pragma unroll
;                 for (int bj = 0; bj < 2; ++bj) { const f32x4 v0 = acc[ai][bj][m][0] * rs, v1 = acc[ai][bj][m][1] * rs;
;                     u32x4 w; w.x = cvt_pk_bf16(v0[0], v0[1]); w.y = cvt_pk_bf16(v0[2], v0[3]); w.z = cvt_pk_bf16(v1[0], v1[1]); w.w = cvt_pk_bf16(v1[2], v1[3]);
;                     *(u32x4*)(O + ((size_t)(u.pn * 2 + bj) * Mrows + row) * HALF + col0) = w; } }
;             asm volatile("" ::: "memory"); }
; template <class Epi, class Sched, bool ALIGN_EPI = false, bool SP2 = false>
; __device__ __forceinline__ void gemm_phase(PG8_LAS unsigned char* lds, const Gemm g, const Sched& S, const Epi& E) {
;     ...
;         if constexpr (ALIGN_EPI) { if (wr == 0) PG8_BAR; }
;         if constexpr (!Epi::AFTER_DRAIN) { E(acc, cur, wr, wc, fr, fq); S.done(cur); }
;         if (!has_next) break;
; #pragma unroll
;         for (int a = 0; a < 2; ++a)
; #pragma unroll
;             for (int b = 0; b < 2; ++b)
; #pragma unroll
;                 for (int m = 0; m < 4; ++m)
; #pragma unroll
;                     for (int n = 0; n < 2; ++n) acc[a][b][m][n] = (f32x4){0.f, 0.f, 0.f, 0.f};
;         cur = nxt; cA = nA; cB = nB; ++ui;
;         if constexpr (ALIGN_EPI) { if (wr == 1) PG8_BAR; }
	s_nop 0
	v_mov_b32_e32 v50, v96
	s_waitcnt vmcnt(6)
	v_mov_b32_e32 v51, v100
	v_mov_b32_e32 v100, v97
	v_mov_b32_e32 v52, v98
	v_mov_b32_e32 v53, v102
	v_mov_b32_e32 v102, v99
	v_pk_add_f32 v[50:51], v[50:51], v[100:101]
	v_pk_add_f32 v[52:53], v[52:53], v[102:103]
	s_nop 0
	v_pk_add_f32 v[50:51], v[50:51], v[52:53]
	s_nop 0
	v_add_f32_e32 v50, v50, v51
	ds_bpermute_b32 v51, v180, v50
	s_waitcnt lgkmcnt(0)
	v_add_f32_e32 v50, v50, v51
	ds_bpermute_b32 v51, v179, v50
	s_waitcnt lgkmcnt(0)
	v_add_f32_e32 v50, v50, v51
	v_fmamk_f32 v50, v50, 0x3a000000, v215
	v_rsq_f32_e32 v50, v50
	s_nop 0
	v_pk_mul_f32 v[46:47], v[46:47], v[50:51] op_sel_hi:[1,0]
	v_pk_mul_f32 v[52:53], v[44:45], v[50:51] op_sel_hi:[1,0]
	v_pk_mul_f32 v[44:45], v[42:43], v[50:51] op_sel_hi:[1,0]
	v_cvt_pk_bf16_f32 v42, v46, v47
	v_lshl_add_u64 v[46:47], s[34:35], 0, v[86:87]
	v_lshlrev_b64 v[46:47], 8, v[46:47]
	v_pk_mul_f32 v[48:49], v[48:49], v[50:51] op_sel_hi:[1,0]
	v_lshl_add_u64 v[46:47], v[160:161], 0, v[46:47]
	v_cvt_pk_bf16_f32 v43, v48, v49
	v_pk_mul_f32 v[38:39], v[38:39], v[50:51] op_sel_hi:[1,0]
	v_cvt_pk_bf16_f32 v44, v44, v45
	v_cvt_pk_bf16_f32 v45, v52, v53
	global_store_dwordx4 v[46:47], v[42:45], off
	v_pk_mul_f32 v[40:41], v[40:41], v[50:51] op_sel_hi:[1,0]
	s_nop 0
	v_pk_mul_f32 v[42:43], v[36:37], v[50:51] op_sel_hi:[1,0]
	v_pk_mul_f32 v[36:37], v[34:35], v[50:51] op_sel_hi:[1,0]
	v_cvt_pk_bf16_f32 v34, v38, v39
	v_lshl_add_u64 v[38:39], s[36:37], 0, v[86:87]
	v_lshlrev_b64 v[38:39], 8, v[38:39]
	v_cvt_pk_bf16_f32 v35, v40, v41
	v_cvt_pk_bf16_f32 v36, v36, v37
	v_cvt_pk_bf16_f32 v37, v42, v43
	v_lshl_add_u64 v[38:39], v[160:161], 0, v[38:39]
	s_mov_b64 exec, s[80:81]
	global_store_dwordx4 v[38:39], v[34:37], off
	s_mov_b64 exec, -1
	s_waitcnt vmcnt(7)
	s_nop 0
	v_mov_b32_e32 v34, v78
	s_waitcnt vmcnt(6)
	v_mov_b32_e32 v35, v74
	v_mov_b32_e32 v74, v79
	v_mov_b32_e32 v36, v80
	v_mov_b32_e32 v37, v76
	v_mov_b32_e32 v76, v81
	v_pk_add_f32 v[34:35], v[34:35], v[74:75]
	v_pk_add_f32 v[36:37], v[36:37], v[76:77]
	s_nop 0
	v_pk_add_f32 v[34:35], v[34:35], v[36:37]
	s_nop 0
	v_add_f32_e32 v34, v34, v35
	ds_bpermute_b32 v35, v180, v34
	s_waitcnt lgkmcnt(0)
	v_add_f32_e32 v34, v34, v35
	ds_bpermute_b32 v35, v179, v34
	s_waitcnt lgkmcnt(0)
	v_add_f32_e32 v34, v34, v35
	v_fmamk_f32 v34, v34, 0x3a000000, v215
	v_rsq_f32_e32 v34, v34
	s_nop 0
	v_pk_mul_f32 v[30:31], v[30:31], v[34:35] op_sel_hi:[1,0]
	v_pk_mul_f32 v[36:37], v[28:29], v[34:35] op_sel_hi:[1,0]
	v_pk_mul_f32 v[28:29], v[26:27], v[34:35] op_sel_hi:[1,0]
	v_cvt_pk_bf16_f32 v26, v30, v31
	v_lshl_add_u64 v[30:31], s[34:35], 0, v[84:85]
	v_lshlrev_b64 v[30:31], 8, v[30:31]
	v_pk_mul_f32 v[32:33], v[32:33], v[34:35] op_sel_hi:[1,0]
	v_lshl_add_u64 v[30:31], v[160:161], 0, v[30:31]
	v_cvt_pk_bf16_f32 v27, v32, v33
	v_pk_mul_f32 v[22:23], v[22:23], v[34:35] op_sel_hi:[1,0]
	v_cvt_pk_bf16_f32 v28, v28, v29
	v_cvt_pk_bf16_f32 v29, v36, v37
	global_store_dwordx4 v[30:31], v[26:29], off
	v_pk_mul_f32 v[24:25], v[24:25], v[34:35] op_sel_hi:[1,0]
	s_nop 0
	v_pk_mul_f32 v[26:27], v[20:21], v[34:35] op_sel_hi:[1,0]
	v_pk_mul_f32 v[20:21], v[18:19], v[34:35] op_sel_hi:[1,0]
	v_cvt_pk_bf16_f32 v18, v22, v23
	v_lshl_add_u64 v[22:23], s[36:37], 0, v[84:85]
	v_lshlrev_b64 v[22:23], 8, v[22:23]
	v_cvt_pk_bf16_f32 v19, v24, v25
	v_cvt_pk_bf16_f32 v20, v20, v21
	v_cvt_pk_bf16_f32 v21, v26, v27
	v_lshl_add_u64 v[22:23], v[160:161], 0, v[22:23]
	s_mov_b64 exec, s[80:81]
	global_store_dwordx4 v[22:23], v[18:21], off
	s_mov_b64 exec, -1
	s_waitcnt vmcnt(7)
	s_nop 0
	v_mov_b32_e32 v18, v70
	s_waitcnt vmcnt(6)
	v_mov_b32_e32 v19, v66
	v_mov_b32_e32 v66, v71
	v_mov_b32_e32 v20, v72
	v_mov_b32_e32 v21, v68
	v_mov_b32_e32 v68, v73
	v_pk_add_f32 v[18:19], v[18:19], v[66:67]
	v_pk_add_f32 v[20:21], v[20:21], v[68:69]
	s_nop 0
	v_pk_add_f32 v[18:19], v[18:19], v[20:21]
	s_nop 0
	v_add_f32_e32 v18, v18, v19
	ds_bpermute_b32 v19, v180, v18
	s_waitcnt lgkmcnt(0)
	v_add_f32_e32 v18, v18, v19
	ds_bpermute_b32 v19, v179, v18
	s_waitcnt lgkmcnt(0)
	v_add_f32_e32 v18, v18, v19
	v_fmamk_f32 v18, v18, 0x3a000000, v215
	v_rsq_f32_e32 v18, v18
	s_nop 0
	v_pk_mul_f32 v[14:15], v[14:15], v[18:19] op_sel_hi:[1,0]
	v_pk_mul_f32 v[20:21], v[12:13], v[18:19] op_sel_hi:[1,0]
	v_pk_mul_f32 v[12:13], v[10:11], v[18:19] op_sel_hi:[1,0]
	v_cvt_pk_bf16_f32 v10, v14, v15
	v_lshl_add_u64 v[14:15], s[34:35], 0, v[82:83]
	v_lshlrev_b64 v[14:15], 8, v[14:15]
	v_pk_mul_f32 v[16:17], v[16:17], v[18:19] op_sel_hi:[1,0]
	v_lshl_add_u64 v[14:15], v[160:161], 0, v[14:15]
	v_cvt_pk_bf16_f32 v11, v16, v17
	v_pk_mul_f32 v[6:7], v[6:7], v[18:19] op_sel_hi:[1,0]
	v_cvt_pk_bf16_f32 v12, v12, v13
	v_cvt_pk_bf16_f32 v13, v20, v21
	global_store_dwordx4 v[14:15], v[10:13], off
	v_pk_mul_f32 v[8:9], v[8:9], v[18:19] op_sel_hi:[1,0]
	s_mov_b64 s[34:35], -1
	v_pk_mul_f32 v[10:11], v[4:5], v[18:19] op_sel_hi:[1,0]
	v_pk_mul_f32 v[4:5], v[2:3], v[18:19] op_sel_hi:[1,0]
	v_cvt_pk_bf16_f32 v2, v6, v7
	v_lshl_add_u64 v[6:7], s[36:37], 0, v[82:83]
	v_lshlrev_b64 v[6:7], 8, v[6:7]
	v_lshl_add_u64 v[6:7], v[160:161], 0, v[6:7]
	v_cvt_pk_bf16_f32 v3, v8, v9
	v_cvt_pk_bf16_f32 v4, v4, v5
	v_cvt_pk_bf16_f32 v5, v10, v11
	s_mov_b64 exec, s[80:81]
	global_store_dwordx4 v[6:7], v[2:5], off
	s_mov_b64 exec, -1
	s_cbranch_vccnz .LBB0_210
	s_andn2_b64 vcc, exec, s[0:1]
	s_cbranch_vccnz .LBB0_209
	s_barrier
	s_branch .LBB0_209
; #define PG8_STAGE(bufoff, gbase, voff) do { _Pragma("unroll") for (int _i = 0; _i < 2; ++_i) \
;         __builtin_amdgcn_global_load_lds((const unsigned*)((const char*)(gbase) + (voff)[_i]), (PG8_LAS unsigned*)(lds + (bufoff) + ldsw + _i * 8192), 16, 0, 0); } while (0)
; #define PG8_LDA(dst, b, h) do { _Pragma("unroll") for (int m = 0; m < 4; ++m) _Pragma("unroll") for (int k = 0; k < 2; ++k) dst[m][k] = *(const PG8_LAS bf16x8*)(lds + PG8_SA(b, h) + aoff + m * 2048 + k * 1024); } while (0)
; #define PG8_LDB(dst, b, h) do { _Pragma("unroll") for (int n = 0; n < 2; ++n) _Pragma("unroll") for (int k = 0; k < 2; ++k) dst[n][k] = *(const PG8_LAS bf16x8*)(lds + PG8_SB(b, h) + boff + n * 2048 + k * 1024); } while (0)
; #define PG8_MMA(ai, bj, At, Bt) do { __builtin_amdgcn_s_setprio(1); _Pragma("unroll") for (int m = 0; m < 4; ++m) _Pragma("unroll") for (int n = 0; n < 2; ++n) _Pragma("unroll") for (int k = 0; k < 2; ++k) \
;         acc[ai][bj][m][n] = __builtin_amdgcn_mfma_f32_16x16x32_bf16(Bt[n][k], At[m][k], acc[ai][bj][m][n], 0, 0, 0); __builtin_amdgcn_s_setprio(0); } while (0)
; #define PG8_WAIT_V(n) asm volatile("s_waitcnt vmcnt(" #n ")" ::: "memory")
; #define PG8_WAIT_L(n) asm volatile("s_waitcnt lgkmcnt(" #n ")" ::: "memory")
; #define PG8_BAR __builtin_amdgcn_s_barrier()
; #define PG8_SCHED __builtin_amdgcn_sched_barrier(0)
; template <class Epi, class Sched, bool ALIGN_EPI = false, bool SP2 = false>
; __device__ __forceinline__ void gemm_phase(PG8_LAS unsigned char* lds, const Gemm g, const Sched& S, const Epi& E) {
;     ...
;             if constexpr (SP2) {
;             PG8_LDB(B0, 0, 0); PG8_LDB(B1, 0, 1); PG8_SCHED; PG8_LDA(At, 0, 0); PG8_STAGE(PG8_SA(1, 1), a1 + hstep, voffA);
;             PG8_WAIT_V(8); PG8_WAIT_L(0); PG8_BAR; PG8_MMA(0, 0, At, B0); PG8_MMA(0, 1, At, B1); PG8_BAR; PG8_SCHED;
;             PG8_LDA(At, 0, 1); PG8_STAGE(PG8_SB(0, 0), b2, voffB); PG8_STAGE(PG8_SB(0, 1), b2 + hstep, voffB); PG8_STAGE(PG8_SA(0, 0), a2, voffA);
;             PG8_WAIT_V(8); PG8_WAIT_L(0); PG8_BAR; PG8_MMA(1, 0, At, B0); PG8_MMA(1, 1, At, B1); PG8_BAR; PG8_SCHED;
.Ltail_loop:
	v_add_u32_e32 v134, s88, v177
	ds_read_b128 v[114:117], v134
	ds_read_b128 v[118:121], v134 offset:1024
	ds_read_b128 v[130:133], v134 offset:2048
	ds_read_b128 v[134:137], v134 offset:3072
	s_add_u32 s40, s34, 0xfff80080
	s_addc_u32 s41, s35, -1
	s_cmp_eq_u32 s46, 28
	s_cselect_b32 s43, s15, s41
	s_cselect_b32 s42, s19, s40
	s_cselect_b32 s41, s17, s45
	s_cselect_b32 s40, s37, s44
	v_lshl_add_u64 v[204:205], s[34:35], 0, v[164:165]
	s_add_i32 m0, s8, 0xc000
	ds_read_b128 v[180:183], v178
	ds_read_b128 v[184:187], v178 offset:1024
	ds_read_b128 v[188:191], v178 offset:2048
	ds_read_b128 v[192:195], v178 offset:3072
	ds_read_b128 v[196:199], v178 offset:4096
	ds_read_b128 v[200:203], v178 offset:5120
	ds_read_b128 v[208:211], v178 offset:6144
	ds_read_b128 v[230:233], v178 offset:7168
	global_load_lds_dwordx4 v[204:205], off
	v_lshl_add_u64 v[204:205], s[34:35], 0, v[166:167]
	s_add_i32 m0, s8, 0xe000
	s_nop 0
	global_load_lds_dwordx4 v[204:205], off
	s_waitcnt vmcnt(8)
	s_waitcnt lgkmcnt(0)
	s_barrier
	s_setprio 1
	s_waitcnt lgkmcnt(0)
	v_mfma_f32_16x16x32_bf16 v[142:145], v[114:117], v[180:183], v[142:145]
	v_mfma_f32_16x16x32_bf16 v[138:141], v[130:133], v[180:183], v[138:141]
	v_mfma_f32_16x16x32_bf16 v[110:113], v[114:117], v[188:191], v[110:113]
	v_mfma_f32_16x16x32_bf16 v[106:109], v[130:133], v[188:191], v[106:109]
	v_mfma_f32_16x16x32_bf16 v[94:97], v[114:117], v[196:199], v[94:97]
	v_mfma_f32_16x16x32_bf16 v[90:93], v[130:133], v[196:199], v[90:93]
	v_mfma_f32_16x16x32_bf16 v[78:81], v[114:117], v[208:211], v[78:81]
	v_mfma_f32_16x16x32_bf16 v[74:77], v[130:133], v[208:211], v[74:77]
	v_mfma_f32_16x16x32_bf16 v[142:145], v[118:121], v[184:187], v[142:145]
	v_mfma_f32_16x16x32_bf16 v[138:141], v[134:137], v[184:187], v[138:141]
	v_mfma_f32_16x16x32_bf16 v[110:113], v[118:121], v[192:195], v[110:113]
	v_mfma_f32_16x16x32_bf16 v[106:109], v[134:137], v[192:195], v[106:109]
	v_mfma_f32_16x16x32_bf16 v[94:97], v[118:121], v[200:203], v[94:97]
	v_mfma_f32_16x16x32_bf16 v[90:93], v[134:137], v[200:203], v[90:93]
	v_mfma_f32_16x16x32_bf16 v[78:81], v[118:121], v[230:233], v[78:81]
	v_mfma_f32_16x16x32_bf16 v[74:77], v[134:137], v[230:233], v[74:77]
	s_setprio 0
	s_setprio 1
	s_setprio 0
	s_barrier
	s_add_i32 s47, s88, s6
	v_lshl_add_u64 v[204:205], s[40:41], 0, v[0:1]
	s_mov_b32 m0, s47
	ds_read_b128 v[180:183], v178 offset:16384
	ds_read_b128 v[184:187], v178 offset:17408
	ds_read_b128 v[188:191], v178 offset:18432
	ds_read_b128 v[192:195], v178 offset:19456
	ds_read_b128 v[196:199], v178 offset:20480
	ds_read_b128 v[200:203], v178 offset:21504
	ds_read_b128 v[208:211], v178 offset:22528
	ds_read_b128 v[230:233], v178 offset:23552
	global_load_lds_dwordx4 v[204:205], off
	s_add_i32 m0, s47, 0x2000
	s_add_u32 s50, s40, 0x80000
	v_lshl_add_u64 v[212:213], s[40:41], 0, v[154:155]
	s_addc_u32 s51, s41, 0
	s_add_i32 s47, s89, s6
	global_load_lds_dwordx4 v[212:213], off
	v_lshl_add_u64 v[234:235], s[50:51], 0, v[0:1]
	s_mov_b32 m0, s47
	v_lshl_add_u64 v[236:237], s[42:43], 0, v[156:157]
	global_load_lds_dwordx4 v[234:235], off
	v_lshl_add_u64 v[234:235], s[50:51], 0, v[154:155]
	s_add_i32 m0, s47, 0x2000
	s_nop 0
	global_load_lds_dwordx4 v[234:235], off
	v_lshl_add_u64 v[234:235], s[42:43], 0, v[158:159]
	s_mov_b32 m0, s8
	s_nop 0
	global_load_lds_dwordx4 v[234:235], off
	s_mov_b32 m0, s9
	s_nop 0
	global_load_lds_dwordx4 v[236:237], off
	s_waitcnt vmcnt(8)
	s_waitcnt lgkmcnt(0)
	s_barrier
	s_setprio 1
	s_waitcnt lgkmcnt(0)
	v_mfma_f32_16x16x32_bf16 v[62:65], v[114:117], v[180:183], v[62:65]
	v_mfma_f32_16x16x32_bf16 v[58:61], v[130:133], v[180:183], v[58:61]
	v_mfma_f32_16x16x32_bf16 v[46:49], v[114:117], v[188:191], v[46:49]
	v_mfma_f32_16x16x32_bf16 v[42:45], v[130:133], v[188:191], v[42:45]
	v_mfma_f32_16x16x32_bf16 v[30:33], v[114:117], v[196:199], v[30:33]
	v_mfma_f32_16x16x32_bf16 v[26:29], v[130:133], v[196:199], v[26:29]
	v_mfma_f32_16x16x32_bf16 v[14:17], v[114:117], v[208:211], v[14:17]
	v_mfma_f32_16x16x32_bf16 v[10:13], v[130:133], v[208:211], v[10:13]
	v_mfma_f32_16x16x32_bf16 v[62:65], v[118:121], v[184:187], v[62:65]
	v_mfma_f32_16x16x32_bf16 v[58:61], v[134:137], v[184:187], v[58:61]
	v_mfma_f32_16x16x32_bf16 v[46:49], v[118:121], v[192:195], v[46:49]
	v_mfma_f32_16x16x32_bf16 v[42:45], v[134:137], v[192:195], v[42:45]
	v_mfma_f32_16x16x32_bf16 v[30:33], v[118:121], v[200:203], v[30:33]
	v_mfma_f32_16x16x32_bf16 v[26:29], v[134:137], v[200:203], v[26:29]
	v_mfma_f32_16x16x32_bf16 v[14:17], v[118:121], v[230:233], v[14:17]
	v_mfma_f32_16x16x32_bf16 v[10:13], v[134:137], v[230:233], v[10:13]
	s_setprio 0
	s_setprio 1
	s_setprio 0
	s_barrier
; #define PG8_STAGE(bufoff, gbase, voff) do { _Pragma("unroll") for (int _i = 0; _i < 2; ++_i) \
;         __builtin_amdgcn_global_load_lds((const unsigned*)((const char*)(gbase) + (voff)[_i]), (PG8_LAS unsigned*)(lds + (bufoff) + ldsw + _i * 8192), 16, 0, 0); } while (0)
; #define PG8_LDA(dst, b, h) do { _Pragma("unroll") for (int m = 0; m < 4; ++m) _Pragma("unroll") for (int k = 0; k < 2; ++k) dst[m][k] = *(const PG8_LAS bf16x8*)(lds + PG8_SA(b, h) + aoff + m * 2048 + k * 1024); } while (0)
; #define PG8_LDB(dst, b, h) do { _Pragma("unroll") for (int n = 0; n < 2; ++n) _Pragma("unroll") for (int k = 0; k < 2; ++k) dst[n][k] = *(const PG8_LAS bf16x8*)(lds + PG8_SB(b, h) + boff + n * 2048 + k * 1024); } while (0)
; #define PG8_MMA(ai, bj, At, Bt) do { __builtin_amdgcn_s_setprio(1); _Pragma("unroll") for (int m = 0; m < 4; ++m) _Pragma("unroll") for (int n = 0; n < 2; ++n) _Pragma("unroll") for (int k = 0; k < 2; ++k) \
;         acc[ai][bj][m][n] = __builtin_amdgcn_mfma_f32_16x16x32_bf16(Bt[n][k], At[m][k], acc[ai][bj][m][n], 0, 0, 0); __builtin_amdgcn_s_setprio(0); } while (0)
; #define PG8_WAIT_V(n) asm volatile("s_waitcnt vmcnt(" #n ")" ::: "memory")
; #define PG8_WAIT_L(n) asm volatile("s_waitcnt lgkmcnt(" #n ")" ::: "memory")
; #define PG8_BAR __builtin_amdgcn_s_barrier()
; #define PG8_SCHED __builtin_amdgcn_sched_barrier(0)
; template <class Epi, class Sched, bool ALIGN_EPI = false, bool SP2 = false>
; __device__ __forceinline__ void gemm_phase(PG8_LAS unsigned char* lds, const Gemm g, const Sched& S, const Epi& E) {
;     ...
;             PG8_LDB(B0, 1, 0); PG8_LDB(B1, 1, 1); PG8_SCHED; PG8_LDA(At, 1, 0); PG8_STAGE(PG8_SA(0, 1), a2 + hstep, voffA);
;             PG8_WAIT_V(8); PG8_WAIT_L(0); PG8_BAR; PG8_MMA(0, 0, At, B0); PG8_MMA(0, 1, At, B1); PG8_BAR; PG8_SCHED;
;             PG8_LDA(At, 1, 1); PG8_STAGE(PG8_SB(1, 0), b3, voffB); PG8_STAGE(PG8_SB(1, 1), b3 + hstep, voffB); PG8_STAGE(PG8_SA(1, 0), a3, voffA);
;             PG8_WAIT_V(8); PG8_WAIT_L(0); PG8_BAR; PG8_MMA(1, 0, At, B0); PG8_MMA(1, 1, At, B1); PG8_BAR; PG8_SCHED;
	s_add_i32 s47, 0, 0x1c000
	v_add_u32_e32 v134, s90, v177
	ds_read_b128 v[114:117], v134
	ds_read_b128 v[118:121], v134 offset:1024
	ds_read_b128 v[130:133], v134 offset:2048
	ds_read_b128 v[134:137], v134 offset:3072
	s_add_u32 s42, s42, 0x80000
	s_addc_u32 s43, s43, 0
	s_mov_b32 m0, s10
	v_lshl_add_u64 v[238:239], s[42:43], 0, v[158:159]
	ds_read_b128 v[180:183], v178 offset:32768
	ds_read_b128 v[184:187], v178 offset:33792
	ds_read_b128 v[188:191], v178 offset:34816
	ds_read_b128 v[192:195], v178 offset:35840
	ds_read_b128 v[196:199], v178 offset:36864
	ds_read_b128 v[200:203], v178 offset:37888
	ds_read_b128 v[208:211], v178 offset:38912
	ds_read_b128 v[230:233], v178 offset:39936
	global_load_lds_dwordx4 v[238:239], off
	v_lshl_add_u64 v[238:239], s[42:43], 0, v[156:157]
	s_mov_b32 m0, s11
	s_nop 0
	global_load_lds_dwordx4 v[238:239], off
	s_waitcnt vmcnt(8)
	s_waitcnt lgkmcnt(0)
	s_barrier
	s_setprio 1
	s_waitcnt lgkmcnt(0)
	v_mfma_f32_16x16x32_bf16 v[142:145], v[114:117], v[180:183], v[142:145]
	v_mfma_f32_16x16x32_bf16 v[138:141], v[130:133], v[180:183], v[138:141]
	v_mfma_f32_16x16x32_bf16 v[110:113], v[114:117], v[188:191], v[110:113]
	v_mfma_f32_16x16x32_bf16 v[106:109], v[130:133], v[188:191], v[106:109]
	v_mfma_f32_16x16x32_bf16 v[94:97], v[114:117], v[196:199], v[94:97]
	v_mfma_f32_16x16x32_bf16 v[90:93], v[130:133], v[196:199], v[90:93]
	v_mfma_f32_16x16x32_bf16 v[78:81], v[114:117], v[208:211], v[78:81]
	v_mfma_f32_16x16x32_bf16 v[74:77], v[130:133], v[208:211], v[74:77]
	v_mfma_f32_16x16x32_bf16 v[142:145], v[118:121], v[184:187], v[142:145]
	v_mfma_f32_16x16x32_bf16 v[138:141], v[134:137], v[184:187], v[138:141]
	v_mfma_f32_16x16x32_bf16 v[110:113], v[118:121], v[192:195], v[110:113]
	v_mfma_f32_16x16x32_bf16 v[106:109], v[134:137], v[192:195], v[106:109]
	v_mfma_f32_16x16x32_bf16 v[94:97], v[118:121], v[200:203], v[94:97]
	v_mfma_f32_16x16x32_bf16 v[90:93], v[134:137], v[200:203], v[90:93]
	v_mfma_f32_16x16x32_bf16 v[78:81], v[118:121], v[230:233], v[78:81]
	v_mfma_f32_16x16x32_bf16 v[74:77], v[134:137], v[230:233], v[74:77]
	s_setprio 0
	s_setprio 1
	s_setprio 0
	s_barrier
	s_add_i32 s42, s90, s6
	v_lshl_add_u64 v[204:205], v[204:205], 0, s[70:71]
	s_mov_b32 m0, s42
	ds_read_b128 v[180:183], v178 offset:49152
	ds_read_b128 v[184:187], v178 offset:50176
	ds_read_b128 v[188:191], v178 offset:51200
	ds_read_b128 v[192:195], v178 offset:52224
	ds_read_b128 v[196:199], v178 offset:53248
	ds_read_b128 v[200:203], v178 offset:54272
	ds_read_b128 v[208:211], v178 offset:55296
	ds_read_b128 v[230:233], v178 offset:56320
	global_load_lds_dwordx4 v[204:205], off
	s_add_i32 m0, s42, 0x2000
	s_add_u32 s40, s40, 0x80080
	v_lshl_add_u64 v[204:205], v[212:213], 0, s[70:71]
	s_addc_u32 s41, s41, 0
	s_add_i32 s42, s47, s6
	global_load_lds_dwordx4 v[204:205], off
	v_lshl_add_u64 v[204:205], s[40:41], 0, v[0:1]
	s_mov_b32 m0, s42
	s_nop 0
	global_load_lds_dwordx4 v[204:205], off
	v_lshl_add_u64 v[204:205], s[40:41], 0, v[154:155]
	s_add_i32 m0, s42, 0x2000
	s_nop 0
	global_load_lds_dwordx4 v[204:205], off
	v_lshl_add_u64 v[204:205], v[234:235], 0, s[70:71]
	s_mov_b32 m0, s13
	s_nop 0
	global_load_lds_dwordx4 v[204:205], off
	v_lshl_add_u64 v[204:205], v[236:237], 0, s[70:71]
	s_mov_b32 m0, s25
	s_nop 0
	global_load_lds_dwordx4 v[204:205], off
	s_waitcnt vmcnt(8)
	s_waitcnt lgkmcnt(0)
	s_barrier
	s_setprio 1
	s_waitcnt lgkmcnt(0)
	v_mfma_f32_16x16x32_bf16 v[62:65], v[114:117], v[180:183], v[62:65]
	v_mfma_f32_16x16x32_bf16 v[58:61], v[130:133], v[180:183], v[58:61]
	v_mfma_f32_16x16x32_bf16 v[46:49], v[114:117], v[188:191], v[46:49]
	v_mfma_f32_16x16x32_bf16 v[42:45], v[130:133], v[188:191], v[42:45]
	v_mfma_f32_16x16x32_bf16 v[30:33], v[114:117], v[196:199], v[30:33]
	v_mfma_f32_16x16x32_bf16 v[26:29], v[130:133], v[196:199], v[26:29]
	v_mfma_f32_16x16x32_bf16 v[14:17], v[114:117], v[208:211], v[14:17]
	v_mfma_f32_16x16x32_bf16 v[10:13], v[130:133], v[208:211], v[10:13]
	v_mfma_f32_16x16x32_bf16 v[62:65], v[118:121], v[184:187], v[62:65]
	v_mfma_f32_16x16x32_bf16 v[58:61], v[134:137], v[184:187], v[58:61]
	v_mfma_f32_16x16x32_bf16 v[46:49], v[118:121], v[192:195], v[46:49]
	v_mfma_f32_16x16x32_bf16 v[42:45], v[134:137], v[192:195], v[42:45]
	v_mfma_f32_16x16x32_bf16 v[30:33], v[118:121], v[200:203], v[30:33]
	v_mfma_f32_16x16x32_bf16 v[26:29], v[134:137], v[200:203], v[26:29]
	v_mfma_f32_16x16x32_bf16 v[14:17], v[118:121], v[230:233], v[14:17]
	v_mfma_f32_16x16x32_bf16 v[10:13], v[134:137], v[230:233], v[10:13]
	s_setprio 0
	s_setprio 1
	s_setprio 0
	s_barrier
	s_add_i32 s46, s46, 2
	s_add_u32 s34, s34, 0x100
	s_addc_u32 s35, s35, 0
	s_add_u32 s44, s44, 0x100
	s_addc_u32 s45, s45, 0
	s_cmp_gt_u32 s46, 29
	s_cbranch_scc0 .Ltail_loop
	s_branch .Ltail_join
